# work queues: when the own queue runs dry, all eight counters are read once and drained queues are skipped without atomic + barriers
# speedup vs baseline: 1.0048x; 1.0048x over previous
; DI void phase_att(const Params& P, char* lds, int hb, int layer) {
;     ...
;     for (int dq = 0; dq < 8; ++dq) {
;         const int qx = (blockIdx.x + dq) & 7;
;         while (true) {
;             if (tid == 0) *slot = (int)atomicAdd(&ctr[qx], 1u);
;             __syncthreads();
;             const int qi = *slot;
;             __syncthreads();
;             if (qi >= NQ) break;
.LBB0_195:
	s_add_i32 s26, s26, 1
	s_add_i32 s2, s2, 1
	s_cmp_lg_u32 s26, 8
	s_cbranch_scc0 .LBB0_270
	s_cmp_lg_u32 s26, 1
	s_cbranch_scc1 .Lqs_have
	v_cmp_gt_u32_e32 vcc, 8, v174
	s_and_saveexec_b64 s[14:15], vcc
	s_cbranch_execz .Lqs_nopeek
	v_lshlrev_b32_e32 v2, 2, v174
	global_load_dword v3, v2, s[98:99] sc1
	v_mov_b32_e32 v4, s53
	s_waitcnt vmcnt(0)
	v_cmp_lt_i32_e32 vcc, 0x1bf, v3
	s_nop 1
	v_mov_b32_e32 v2, vcc_lo
	ds_write_b32 v4, v2
.Lqs_nopeek:
	s_or_b64 exec, exec, s[14:15]
	v_mov_b32_e32 v4, s53
	s_waitcnt lgkmcnt(0)
	s_barrier
	ds_read_b32 v2, v4
	s_waitcnt lgkmcnt(0)
	v_readfirstlane_b32 s3, v2
	s_nop 3
	v_writelane_b32 v236, s3, 61
	s_barrier
	s_nop 1
.Lqs_have:
	v_readlane_b32 s3, v236, 61
	s_add_i32 s14, s26, s33
	s_and_b32 s14, s14, 7
	s_nop 1
	s_lshr_b32 s3, s3, s14
	s_and_b32 s3, s3, 1
	s_cmp_eq_u32 s3, 1
	s_cbranch_scc1 .LBB0_195
